# hand-written SwiGLU epilogue: packed f32 scale/+1, transcendental ops interleaved 1:1 with packed ops, one address add per store
# speedup vs baseline: 1.0097x; 1.0097x over previous
.LBB0_249:
	v_lshl_add_u32 v148, s26, 8, v144
	v_lshl_or_b32 v142, s27, 7, v146
	v_ashrrev_i32_e32 v143, 31, v142
	v_mov_b64_e32 v[140:141], s[14:15]
	v_mad_i64_i32 v[150:151], s[26:27], v148, s88, v[140:141]
	v_lshlrev_b64 v[142:143], 1, v[142:143]
	v_mov_b32_e32 v172, 0xbfb8aa3b
	v_mov_b32_e32 v173, 1.0
	v_lshl_add_u64 v[150:151], v[150:151], 0, v[142:143]
	s_mov_b64 s[26:27], -1
	v_pk_mul_f32 v[160:161], v[126:127], v[172:173] op_sel_hi:[1,0]
	v_exp_f32_e32 v160, v160
	v_pk_mul_f32 v[162:163], v[128:129], v[172:173] op_sel_hi:[1,0]
	v_exp_f32_e32 v161, v161
	v_pk_mul_f32 v[164:165], v[118:119], v[172:173] op_sel_hi:[1,0]
	v_exp_f32_e32 v162, v162
	v_pk_add_f32 v[160:161], v[160:161], v[172:173] op_sel:[0,1] op_sel_hi:[1,1]
	v_rcp_f32_e32 v160, v160
	v_pk_mul_f32 v[166:167], v[120:121], v[172:173] op_sel_hi:[1,0]
	v_rcp_f32_e32 v161, v161
	s_mov_b64 s[100:101], 0x16000
	v_lshl_add_u64 v[176:177], v[150:151], 0, s[100:101]
	v_exp_f32_e32 v163, v163
	v_pk_mul_f32 v[126:127], v[126:127], v[160:161]
	v_exp_f32_e32 v164, v164
	v_pk_mul_f32 v[122:123], v[122:123], v[126:127]
	v_exp_f32_e32 v165, v165
	v_cvt_pk_bf16_f32 v152, v122, v123
	v_exp_f32_e32 v166, v166
	v_pk_add_f32 v[162:163], v[162:163], v[172:173] op_sel:[0,1] op_sel_hi:[1,1]
	v_rcp_f32_e32 v162, v162
	v_pk_add_f32 v[164:165], v[164:165], v[172:173] op_sel:[0,1] op_sel_hi:[1,1]
	v_rcp_f32_e32 v163, v163
	v_pk_mul_f32 v[168:169], v[110:111], v[172:173] op_sel_hi:[1,0]
	v_rcp_f32_e32 v164, v164
	v_pk_mul_f32 v[128:129], v[128:129], v[162:163]
	v_rcp_f32_e32 v165, v165
	v_pk_mul_f32 v[124:125], v[124:125], v[128:129]
	v_exp_f32_e32 v167, v167
	v_cvt_pk_bf16_f32 v153, v124, v125
	v_exp_f32_e32 v168, v168
	v_pk_mul_f32 v[118:119], v[118:119], v[164:165]
	v_exp_f32_e32 v169, v169
	v_pk_mul_f32 v[114:115], v[114:115], v[118:119]
	v_cvt_pk_bf16_f32 v154, v114, v115
	v_pk_add_f32 v[166:167], v[166:167], v[172:173] op_sel:[0,1] op_sel_hi:[1,1]
	v_rcp_f32_e32 v166, v166
	v_pk_add_f32 v[168:169], v[168:169], v[172:173] op_sel:[0,1] op_sel_hi:[1,1]
	v_rcp_f32_e32 v167, v167
	v_pk_mul_f32 v[170:171], v[112:113], v[172:173] op_sel_hi:[1,0]
	v_rcp_f32_e32 v168, v168
	v_pk_mul_f32 v[120:121], v[120:121], v[166:167]
	v_rcp_f32_e32 v169, v169
	v_pk_mul_f32 v[116:117], v[116:117], v[120:121]
	v_exp_f32_e32 v170, v170
	v_cvt_pk_bf16_f32 v155, v116, v117
	global_store_dwordx4 v[150:151], v[152:155], off
	v_exp_f32_e32 v171, v171
	v_pk_mul_f32 v[110:111], v[110:111], v[168:169]
	v_pk_mul_f32 v[106:107], v[106:107], v[110:111]
	v_cvt_pk_bf16_f32 v156, v106, v107
	v_pk_add_f32 v[170:171], v[170:171], v[172:173] op_sel:[0,1] op_sel_hi:[1,1]
	v_rcp_f32_e32 v170, v170
	v_pk_mul_f32 v[160:161], v[102:103], v[172:173] op_sel_hi:[1,0]
	v_rcp_f32_e32 v171, v171
	v_pk_mul_f32 v[162:163], v[104:105], v[172:173] op_sel_hi:[1,0]
	v_exp_f32_e32 v160, v160
	v_pk_mul_f32 v[112:113], v[112:113], v[170:171]
	v_exp_f32_e32 v161, v161
	v_pk_mul_f32 v[108:109], v[108:109], v[112:113]
	v_exp_f32_e32 v162, v162
	v_cvt_pk_bf16_f32 v157, v108, v109
	v_exp_f32_e32 v163, v163
	v_pk_add_f32 v[160:161], v[160:161], v[172:173] op_sel:[0,1] op_sel_hi:[1,1]
	v_rcp_f32_e32 v160, v160
	v_pk_add_f32 v[162:163], v[162:163], v[172:173] op_sel:[0,1] op_sel_hi:[1,1]
	v_rcp_f32_e32 v161, v161
	s_mov_b64 s[100:101], 0x2c000
	v_lshl_add_u64 v[174:175], v[150:151], 0, s[100:101]
	v_rcp_f32_e32 v162, v162
	v_pk_mul_f32 v[102:103], v[102:103], v[160:161]
	v_rcp_f32_e32 v163, v163
	v_pk_mul_f32 v[98:99], v[98:99], v[102:103]
	v_cvt_pk_bf16_f32 v158, v98, v99
	v_pk_mul_f32 v[104:105], v[104:105], v[162:163]
	v_pk_mul_f32 v[100:101], v[100:101], v[104:105]
	v_cvt_pk_bf16_f32 v159, v100, v101
	global_store_dwordx4 v[176:177], v[156:159], off
	v_pk_mul_f32 v[164:165], v[94:95], v[172:173] op_sel_hi:[1,0]
	v_exp_f32_e32 v164, v164
	v_pk_mul_f32 v[166:167], v[96:97], v[172:173] op_sel_hi:[1,0]
	v_exp_f32_e32 v165, v165
	v_pk_mul_f32 v[168:169], v[86:87], v[172:173] op_sel_hi:[1,0]
	v_exp_f32_e32 v166, v166
	v_pk_add_f32 v[164:165], v[164:165], v[172:173] op_sel:[0,1] op_sel_hi:[1,1]
	v_rcp_f32_e32 v164, v164
	v_pk_mul_f32 v[170:171], v[88:89], v[172:173] op_sel_hi:[1,0]
	v_rcp_f32_e32 v165, v165
	s_mov_b64 s[100:101], 0x42000
	v_lshl_add_u64 v[176:177], v[150:151], 0, s[100:101]
	v_exp_f32_e32 v167, v167
	v_pk_mul_f32 v[94:95], v[94:95], v[164:165]
	v_exp_f32_e32 v168, v168
	v_pk_mul_f32 v[90:91], v[90:91], v[94:95]
	v_exp_f32_e32 v169, v169
	v_cvt_pk_bf16_f32 v152, v90, v91
	v_exp_f32_e32 v170, v170
	v_pk_add_f32 v[166:167], v[166:167], v[172:173] op_sel:[0,1] op_sel_hi:[1,1]
	v_rcp_f32_e32 v166, v166
	v_pk_add_f32 v[168:169], v[168:169], v[172:173] op_sel:[0,1] op_sel_hi:[1,1]
	v_rcp_f32_e32 v167, v167
	v_pk_mul_f32 v[160:161], v[78:79], v[172:173] op_sel_hi:[1,0]
	v_rcp_f32_e32 v168, v168
	v_pk_mul_f32 v[96:97], v[96:97], v[166:167]
	v_rcp_f32_e32 v169, v169
	v_pk_mul_f32 v[92:93], v[92:93], v[96:97]
	v_exp_f32_e32 v171, v171
	v_cvt_pk_bf16_f32 v153, v92, v93
	v_exp_f32_e32 v160, v160
	v_pk_mul_f32 v[86:87], v[86:87], v[168:169]
	v_exp_f32_e32 v161, v161
	v_pk_mul_f32 v[82:83], v[82:83], v[86:87]
	v_cvt_pk_bf16_f32 v154, v82, v83
	v_pk_add_f32 v[170:171], v[170:171], v[172:173] op_sel:[0,1] op_sel_hi:[1,1]
	v_rcp_f32_e32 v170, v170
	v_pk_add_f32 v[160:161], v[160:161], v[172:173] op_sel:[0,1] op_sel_hi:[1,1]
	v_rcp_f32_e32 v171, v171
	v_pk_mul_f32 v[162:163], v[80:81], v[172:173] op_sel_hi:[1,0]
	v_rcp_f32_e32 v160, v160
	v_pk_mul_f32 v[88:89], v[88:89], v[170:171]
	v_rcp_f32_e32 v161, v161
	v_pk_mul_f32 v[84:85], v[84:85], v[88:89]
	v_exp_f32_e32 v162, v162
	v_cvt_pk_bf16_f32 v155, v84, v85
	global_store_dwordx4 v[174:175], v[152:155], off
	v_exp_f32_e32 v163, v163
	v_pk_mul_f32 v[78:79], v[78:79], v[160:161]
	v_pk_mul_f32 v[74:75], v[74:75], v[78:79]
	v_cvt_pk_bf16_f32 v156, v74, v75
	v_pk_add_f32 v[162:163], v[162:163], v[172:173] op_sel:[0,1] op_sel_hi:[1,1]
	v_rcp_f32_e32 v162, v162
	v_pk_mul_f32 v[164:165], v[70:71], v[172:173] op_sel_hi:[1,0]
	v_rcp_f32_e32 v163, v163
	v_pk_mul_f32 v[166:167], v[72:73], v[172:173] op_sel_hi:[1,0]
	v_exp_f32_e32 v164, v164
	v_pk_mul_f32 v[80:81], v[80:81], v[162:163]
	v_exp_f32_e32 v165, v165
	v_pk_mul_f32 v[76:77], v[76:77], v[80:81]
	v_exp_f32_e32 v166, v166
	v_cvt_pk_bf16_f32 v157, v76, v77
	v_exp_f32_e32 v167, v167
	v_pk_add_f32 v[164:165], v[164:165], v[172:173] op_sel:[0,1] op_sel_hi:[1,1]
	v_rcp_f32_e32 v164, v164
	v_pk_add_f32 v[166:167], v[166:167], v[172:173] op_sel:[0,1] op_sel_hi:[1,1]
	v_rcp_f32_e32 v165, v165
	s_mov_b64 s[100:101], 0xb0000
	v_lshl_add_u64 v[174:175], v[150:151], 0, s[100:101]
	v_rcp_f32_e32 v166, v166
	v_pk_mul_f32 v[70:71], v[70:71], v[164:165]
	v_rcp_f32_e32 v167, v167
	v_pk_mul_f32 v[66:67], v[66:67], v[70:71]
	v_cvt_pk_bf16_f32 v158, v66, v67
	v_pk_mul_f32 v[72:73], v[72:73], v[166:167]
	v_pk_mul_f32 v[68:69], v[68:69], v[72:73]
	v_cvt_pk_bf16_f32 v159, v68, v69
	global_store_dwordx4 v[176:177], v[156:159], off
	v_pk_mul_f32 v[168:169], v[62:63], v[172:173] op_sel_hi:[1,0]
	v_exp_f32_e32 v168, v168
	v_pk_mul_f32 v[170:171], v[64:65], v[172:173] op_sel_hi:[1,0]
	v_exp_f32_e32 v169, v169
	v_pk_mul_f32 v[160:161], v[54:55], v[172:173] op_sel_hi:[1,0]
	v_exp_f32_e32 v170, v170
	v_pk_add_f32 v[168:169], v[168:169], v[172:173] op_sel:[0,1] op_sel_hi:[1,1]
	v_rcp_f32_e32 v168, v168
	v_pk_mul_f32 v[162:163], v[56:57], v[172:173] op_sel_hi:[1,0]
	v_rcp_f32_e32 v169, v169
	s_mov_b64 s[100:101], 0xc6000
	v_lshl_add_u64 v[176:177], v[150:151], 0, s[100:101]
	v_exp_f32_e32 v171, v171
	v_pk_mul_f32 v[62:63], v[62:63], v[168:169]
	v_exp_f32_e32 v160, v160
	v_pk_mul_f32 v[58:59], v[58:59], v[62:63]
	v_exp_f32_e32 v161, v161
	v_cvt_pk_bf16_f32 v152, v58, v59
	v_exp_f32_e32 v162, v162
	v_pk_add_f32 v[170:171], v[170:171], v[172:173] op_sel:[0,1] op_sel_hi:[1,1]
	v_rcp_f32_e32 v170, v170
	v_pk_add_f32 v[160:161], v[160:161], v[172:173] op_sel:[0,1] op_sel_hi:[1,1]
	v_rcp_f32_e32 v171, v171
	v_pk_mul_f32 v[164:165], v[46:47], v[172:173] op_sel_hi:[1,0]
	v_rcp_f32_e32 v160, v160
	v_pk_mul_f32 v[64:65], v[64:65], v[170:171]
	v_rcp_f32_e32 v161, v161
	v_pk_mul_f32 v[60:61], v[60:61], v[64:65]
	v_exp_f32_e32 v163, v163
	v_cvt_pk_bf16_f32 v153, v60, v61
	v_exp_f32_e32 v164, v164
	v_pk_mul_f32 v[54:55], v[54:55], v[160:161]
	v_exp_f32_e32 v165, v165
	v_pk_mul_f32 v[50:51], v[50:51], v[54:55]
	v_cvt_pk_bf16_f32 v154, v50, v51
	v_pk_add_f32 v[162:163], v[162:163], v[172:173] op_sel:[0,1] op_sel_hi:[1,1]
	v_rcp_f32_e32 v162, v162
	v_pk_add_f32 v[164:165], v[164:165], v[172:173] op_sel:[0,1] op_sel_hi:[1,1]
	v_rcp_f32_e32 v163, v163
	v_pk_mul_f32 v[166:167], v[48:49], v[172:173] op_sel_hi:[1,0]
	v_rcp_f32_e32 v164, v164
	v_pk_mul_f32 v[56:57], v[56:57], v[162:163]
	v_rcp_f32_e32 v165, v165
	v_pk_mul_f32 v[52:53], v[52:53], v[56:57]
	v_exp_f32_e32 v166, v166
	v_cvt_pk_bf16_f32 v155, v52, v53
	global_store_dwordx4 v[174:175], v[152:155], off
	v_exp_f32_e32 v167, v167
	v_pk_mul_f32 v[46:47], v[46:47], v[164:165]
	v_pk_mul_f32 v[42:43], v[42:43], v[46:47]
	v_cvt_pk_bf16_f32 v156, v42, v43
	v_pk_add_f32 v[166:167], v[166:167], v[172:173] op_sel:[0,1] op_sel_hi:[1,1]
	v_rcp_f32_e32 v166, v166
	v_pk_mul_f32 v[168:169], v[38:39], v[172:173] op_sel_hi:[1,0]
	v_rcp_f32_e32 v167, v167
	v_pk_mul_f32 v[170:171], v[40:41], v[172:173] op_sel_hi:[1,0]
	v_exp_f32_e32 v168, v168
	v_pk_mul_f32 v[48:49], v[48:49], v[166:167]
	v_exp_f32_e32 v169, v169
	v_pk_mul_f32 v[44:45], v[44:45], v[48:49]
	v_exp_f32_e32 v170, v170
	v_cvt_pk_bf16_f32 v157, v44, v45
	v_exp_f32_e32 v171, v171
	v_pk_add_f32 v[168:169], v[168:169], v[172:173] op_sel:[0,1] op_sel_hi:[1,1]
	v_rcp_f32_e32 v168, v168
	v_pk_add_f32 v[170:171], v[170:171], v[172:173] op_sel:[0,1] op_sel_hi:[1,1]
	v_rcp_f32_e32 v169, v169
	s_mov_b64 s[100:101], 0xdc000
	v_lshl_add_u64 v[174:175], v[150:151], 0, s[100:101]
	v_rcp_f32_e32 v170, v170
	v_pk_mul_f32 v[38:39], v[38:39], v[168:169]
	v_rcp_f32_e32 v171, v171
	v_pk_mul_f32 v[34:35], v[34:35], v[38:39]
	v_cvt_pk_bf16_f32 v158, v34, v35
	v_pk_mul_f32 v[40:41], v[40:41], v[170:171]
	v_pk_mul_f32 v[36:37], v[36:37], v[40:41]
	v_cvt_pk_bf16_f32 v159, v36, v37
	global_store_dwordx4 v[176:177], v[156:159], off
	v_pk_mul_f32 v[160:161], v[30:31], v[172:173] op_sel_hi:[1,0]
	v_exp_f32_e32 v160, v160
	v_pk_mul_f32 v[162:163], v[32:33], v[172:173] op_sel_hi:[1,0]
	v_exp_f32_e32 v161, v161
	v_pk_mul_f32 v[164:165], v[22:23], v[172:173] op_sel_hi:[1,0]
	v_exp_f32_e32 v162, v162
	v_pk_add_f32 v[160:161], v[160:161], v[172:173] op_sel:[0,1] op_sel_hi:[1,1]
	v_rcp_f32_e32 v160, v160
	v_pk_mul_f32 v[166:167], v[24:25], v[172:173] op_sel_hi:[1,0]
	v_rcp_f32_e32 v161, v161
	s_mov_b64 s[100:101], 0xf2000
	v_lshl_add_u64 v[176:177], v[150:151], 0, s[100:101]
	v_exp_f32_e32 v163, v163
	v_pk_mul_f32 v[30:31], v[30:31], v[160:161]
	v_exp_f32_e32 v164, v164
	v_pk_mul_f32 v[26:27], v[26:27], v[30:31]
	v_exp_f32_e32 v165, v165
	v_cvt_pk_bf16_f32 v152, v26, v27
	v_exp_f32_e32 v166, v166
	v_pk_add_f32 v[162:163], v[162:163], v[172:173] op_sel:[0,1] op_sel_hi:[1,1]
	v_rcp_f32_e32 v162, v162
	v_pk_add_f32 v[164:165], v[164:165], v[172:173] op_sel:[0,1] op_sel_hi:[1,1]
	v_rcp_f32_e32 v163, v163
	v_pk_mul_f32 v[168:169], v[14:15], v[172:173] op_sel_hi:[1,0]
	v_rcp_f32_e32 v164, v164
	v_pk_mul_f32 v[32:33], v[32:33], v[162:163]
	v_rcp_f32_e32 v165, v165
	v_pk_mul_f32 v[28:29], v[28:29], v[32:33]
	v_exp_f32_e32 v167, v167
	v_cvt_pk_bf16_f32 v153, v28, v29
	v_exp_f32_e32 v168, v168
	v_pk_mul_f32 v[22:23], v[22:23], v[164:165]
	v_exp_f32_e32 v169, v169
	v_pk_mul_f32 v[18:19], v[18:19], v[22:23]
	v_cvt_pk_bf16_f32 v154, v18, v19
	v_pk_add_f32 v[166:167], v[166:167], v[172:173] op_sel:[0,1] op_sel_hi:[1,1]
	v_rcp_f32_e32 v166, v166
	v_pk_add_f32 v[168:169], v[168:169], v[172:173] op_sel:[0,1] op_sel_hi:[1,1]
	v_rcp_f32_e32 v167, v167
	v_pk_mul_f32 v[170:171], v[16:17], v[172:173] op_sel_hi:[1,0]
	v_rcp_f32_e32 v168, v168
	v_pk_mul_f32 v[24:25], v[24:25], v[166:167]
	v_rcp_f32_e32 v169, v169
	v_pk_mul_f32 v[20:21], v[20:21], v[24:25]
	v_exp_f32_e32 v170, v170
	v_cvt_pk_bf16_f32 v155, v20, v21
	global_store_dwordx4 v[174:175], v[152:155], off
	v_exp_f32_e32 v171, v171
	v_pk_mul_f32 v[14:15], v[14:15], v[168:169]
	v_pk_mul_f32 v[8:9], v[8:9], v[14:15]
	v_cvt_pk_bf16_f32 v156, v8, v9
	v_pk_add_f32 v[170:171], v[170:171], v[172:173] op_sel:[0,1] op_sel_hi:[1,1]
	v_rcp_f32_e32 v170, v170
	v_pk_mul_f32 v[160:161], v[4:5], v[172:173] op_sel_hi:[1,0]
	v_rcp_f32_e32 v171, v171
	v_pk_mul_f32 v[162:163], v[6:7], v[172:173] op_sel_hi:[1,0]
	v_exp_f32_e32 v160, v160
	v_pk_mul_f32 v[16:17], v[16:17], v[170:171]
	v_exp_f32_e32 v161, v161
	v_pk_mul_f32 v[10:11], v[10:11], v[16:17]
	v_exp_f32_e32 v162, v162
	v_cvt_pk_bf16_f32 v157, v10, v11
	v_exp_f32_e32 v163, v163
	v_pk_add_f32 v[160:161], v[160:161], v[172:173] op_sel:[0,1] op_sel_hi:[1,1]
	v_rcp_f32_e32 v160, v160
	v_pk_add_f32 v[162:163], v[162:163], v[172:173] op_sel:[0,1] op_sel_hi:[1,1]
	v_rcp_f32_e32 v161, v161
	v_rcp_f32_e32 v162, v162
	v_pk_mul_f32 v[4:5], v[4:5], v[160:161]
	v_rcp_f32_e32 v163, v163
	v_pk_mul_f32 v[0:1], v[0:1], v[4:5]
	v_cvt_pk_bf16_f32 v158, v0, v1
	v_pk_mul_f32 v[6:7], v[6:7], v[162:163]
	v_pk_mul_f32 v[2:3], v[2:3], v[6:7]
	v_cvt_pk_bf16_f32 v159, v2, v3
	global_store_dwordx4 v[176:177], v[156:159], off
	s_andn2_b64 vcc, exec, s[0:1]
	s_cbranch_vccnz .LBB0_242
	s_andn2_b64 vcc, exec, s[12:13]
	s_cbranch_vccnz .LBB0_241
	s_barrier
	s_branch .LBB0_241
